# v21
# baseline (speedup 1.0000x reference)
; #define SBAR() __builtin_amdgcn_sched_barrier(0)
; DI void attn_step(const LAS unsigned char* Kb, const LAS unsigned char* Vb, f32x16& c0, f32x16& c1, f32x16& n0, f32x16& n1, bf16x8 (&pf)[2][2],
;                   f32x16 (&o)[4], f32x16& negm, float& mrun, float& lrun, const bf16x8 (&qf)[4]) {
;     ...
;     vf[0] = AT_VF(0); vf[1] = AT_VF(1); vf[2] = AT_VF(2);
;     float pm[4];
; #pragma unroll
;     for (int i = 0; i < 4; ++i) {
;         vf[(i + 3) % 4] = AT_VF(i + 3);
;         o[0] = MFMA32(vf[i % 4], pf[(i >> 1) & 1][i & 1], o[0]);
;         const float a = max3f(AT_C(8 * i), AT_C(8 * i + 1), AT_C(8 * i + 2)), b = max3f(AT_C(8 * i + 3), AT_C(8 * i + 4), AT_C(8 * i + 5));
;         pm[i] = max3f(a, b, __builtin_fmaxf(AT_C(8 * i + 6), AT_C(8 * i + 7)));
;         SBAR();
;     }
;     float mx = __builtin_fmaxf(__builtin_fmaxf(pm[0], pm[1]), __builtin_fmaxf(pm[2], pm[3]));
;     { auto rr = __builtin_amdgcn_permlane32_swap(__float_as_uint(mx), __float_as_uint(mx), false, false); mx = __builtin_fmaxf(__uint_as_float(rr[0]), __uint_as_float(rr[1])); }
;     float sc = 1.0f; bool need = false;
;     if (__builtin_expect(__any(mx > AT_THR), 0)) {
;         const float d = mx > AT_THR ? mx : 0.f;
; #pragma unroll
;         for (int r = 0; r < 16; ++r) { c0[r] -= d; c1[r] -= d; }
;         mrun += d; sc = __builtin_amdgcn_exp2f(-d); need = true;
; #pragma unroll
;         for (int r = 0; r < 16; ++r) negm[r] = -mrun;
;     }
;     asm volatile("" : "+v"(negm));
;     __builtin_amdgcn_s_setprio(1);
; #pragma unroll
;     for (int i = 4; i < 16; ++i) {
;         if (i + 3 < 16) vf[(i + 3) % 4] = AT_VF(i + 3);
;         o[i >> 2] = MFMA32(vf[i % 4], pf[(i >> 1) & 1][i & 1], o[i >> 2]);
;         const int j = i - 4, e0 = j < 8 ? 3 * j : 24 + 2 * (j - 8), ne = j < 8 ? 3 : 2;
; #pragma unroll
;         for (int e = e0; e < e0 + ne; ++e) { if (e < 16) c0[e & 15] = __builtin_amdgcn_exp2f(c0[e & 15]); else c1[e & 15] = __builtin_amdgcn_exp2f(c1[e & 15]); }
;         SBAR();
;     }
;     bf16x8 kf[4];
;     kf[0] = AT_KF(0); kf[1] = AT_KF(1); kf[2] = AT_KF(2);
;     float ls0 = 0.f, ls1 = 0.f; unsigned pw[16];
; #pragma unroll
;     for (int i = 0; i < 8; ++i) {
;         if (i + 3 < 8) kf[(i + 3) % 4] = AT_KF(i + 3);
;         if (i & 1) n1 = MFMA32(kf[i % 4], qf[i >> 1], i < 2 ? negm : n1); else n0 = MFMA32(kf[i % 4], qf[i >> 1], i < 2 ? negm : n0);
.LBB0_457:
	ds_read_b128 v[80:83], v196 offset:36864
	ds_read_b128 v[84:87], v196 offset:36896
	ds_read_b128 v[88:91], v196 offset:36928
	ds_read_b128 v[92:95], v196 offset:36960
	s_add_i32 s5, s68, 2
	s_min_u32 s8, s5, 0x103
	s_cmpk_gt_u32 s68, 0xfd
	s_cselect_b32 s9, s0, 0
	s_add_i32 s9, s9, s8
	s_lshl_b32 s18, s9, 18
	s_cmpk_gt_u32 s68, 0xff
	s_cselect_b32 s8, s0, 0
	s_add_i32 s8, s8, s68
	v_lshl_add_u64 v[240:241], v[188:189], 0, s[18:19]
	s_lshl_b32 s18, s8, 6
	s_lshl_b64 s[8:9], s[18:19], 1
	v_lshl_add_u64 v[242:243], v[190:191], 0, s[8:9]
	global_load_dwordx4 v[168:171], v[240:241], off offset:2048
	global_load_dwordx4 v[164:167], v[242:243], off
	v_lshl_add_u64 v[240:241], v[192:193], 0, s[8:9]
	global_load_dwordx4 v[160:163], v[240:241], off
	s_waitcnt lgkmcnt(3)
	v_mfma_f32_32x32x16_bf16 v[48:63], v[80:83], v[148:151], v[48:63]
	ds_read_b128 v[172:175], v196 offset:41472
	v_max3_f32 v80, v96, v97, v98
	v_max3_f32 v81, v99, v100, v101
	v_max3_f32 v80, v80, v102, v103
	v_max3_f32 v81, v81, v104, v105
	s_waitcnt lgkmcnt(3)
	v_mfma_f32_32x32x16_bf16 v[48:63], v[84:87], v[144:147], v[48:63]
	ds_read_b128 v[176:179], v196 offset:41504
	v_max3_f32 v80, v80, v106, v107
	v_max3_f32 v81, v81, v108, v109
	v_max3_f32 v80, v80, v110, v111
	v_max3_f32 v81, v81, v64, v65
	s_waitcnt lgkmcnt(3)
	v_mfma_f32_32x32x16_bf16 v[48:63], v[88:91], v[152:155], v[48:63]
	ds_read_b128 v[180:183], v196 offset:41536
	v_max3_f32 v80, v80, v66, v67
	v_max3_f32 v81, v81, v68, v69
	v_max3_f32 v80, v80, v70, v71
	v_max3_f32 v81, v81, v72, v73
	s_waitcnt lgkmcnt(3)
	v_mfma_f32_32x32x16_bf16 v[48:63], v[92:95], v[156:159], v[48:63]
	ds_read_b128 v[248:251], v196 offset:41568
	v_max3_f32 v80, v80, v74, v75
	v_max3_f32 v81, v81, v76, v77
	v_max3_f32 v80, v80, v78, v79
	v_max_f32_e32 v80, v80, v81
	v_cmp_lt_f32_e32 vcc, s15, v80
	s_cmp_lg_u64 vcc, 0
	s_cselect_b64 s[8:9], -1, 0
	s_cbranch_vccnz .LBB0_467
.LBB0_459:
	s_setprio 1
	s_waitcnt lgkmcnt(3)
	v_mfma_f32_32x32x16_bf16 v[32:47], v[172:175], v[148:151], v[32:47]
	ds_read_b128 v[80:83], v196 offset:46080
	v_exp_f32_e32 v92, v96
	v_exp_f32_e32 v93, v97
	v_exp_f32_e32 v94, v98
	s_waitcnt lgkmcnt(3)
	v_mfma_f32_32x32x16_bf16 v[32:47], v[176:179], v[144:147], v[32:47]
	ds_read_b128 v[84:87], v196 offset:46112
	v_exp_f32_e32 v95, v99
	v_exp_f32_e32 v172, v100
	v_exp_f32_e32 v173, v101
	s_waitcnt lgkmcnt(3)
	v_mfma_f32_32x32x16_bf16 v[32:47], v[180:183], v[152:155], v[32:47]
	ds_read_b128 v[96:99], v196 offset:46144
	v_exp_f32_e32 v174, v102
	v_exp_f32_e32 v175, v103
	v_exp_f32_e32 v176, v104
	s_waitcnt lgkmcnt(3)
	v_mfma_f32_32x32x16_bf16 v[32:47], v[248:251], v[156:159], v[32:47]
	ds_read_b128 v[100:103], v196 offset:46176
	v_exp_f32_e32 v177, v105
	v_exp_f32_e32 v178, v106
	v_exp_f32_e32 v179, v107
	s_waitcnt lgkmcnt(3)
	v_mfma_f32_32x32x16_bf16 v[16:31], v[80:83], v[148:151], v[16:31]
	ds_read_b128 v[104:107], v196 offset:50688
	v_exp_f32_e32 v180, v108
	v_exp_f32_e32 v181, v109
	v_exp_f32_e32 v182, v110
	s_waitcnt lgkmcnt(3)
	v_mfma_f32_32x32x16_bf16 v[16:31], v[84:87], v[144:147], v[16:31]
	ds_read_b128 v[80:83], v196 offset:50720
	v_exp_f32_e32 v183, v111
	v_exp_f32_e32 v218, v64
	v_exp_f32_e32 v219, v65
	s_waitcnt lgkmcnt(3)
	v_mfma_f32_32x32x16_bf16 v[16:31], v[96:99], v[152:155], v[16:31]
	ds_read_b128 v[96:99], v196 offset:50752
	v_exp_f32_e32 v222, v66
	v_exp_f32_e32 v223, v67
	v_exp_f32_e32 v224, v68
	s_waitcnt lgkmcnt(3)
	v_mfma_f32_32x32x16_bf16 v[16:31], v[100:103], v[156:159], v[16:31]
	ds_read_b128 v[64:67], v196 offset:50784
	v_exp_f32_e32 v225, v69
	v_exp_f32_e32 v226, v70
	v_exp_f32_e32 v227, v71
	s_waitcnt lgkmcnt(3)
	v_mfma_f32_32x32x16_bf16 v[0:15], v[104:107], v[148:151], v[0:15]
	v_exp_f32_e32 v228, v72
	v_exp_f32_e32 v229, v73
	s_waitcnt lgkmcnt(2)
	v_mfma_f32_32x32x16_bf16 v[0:15], v[80:83], v[144:147], v[0:15]
	v_exp_f32_e32 v230, v74
	v_exp_f32_e32 v231, v75
	s_waitcnt lgkmcnt(1)
	v_mfma_f32_32x32x16_bf16 v[0:15], v[96:99], v[152:155], v[0:15]
	v_exp_f32_e32 v232, v76
	v_exp_f32_e32 v233, v77
	s_waitcnt lgkmcnt(0)
	v_mfma_f32_32x32x16_bf16 v[0:15], v[64:67], v[156:159], v[0:15]
	v_exp_f32_e32 v159, v78
	v_exp_f32_e32 v234, v79
	ds_read_b128 v[64:67], v196 offset:9216
	ds_read_b128 v[80:83], v196 offset:9248
	ds_read_b128 v[84:87], v196 offset:13824
	ds_read_b128 v[88:91], v196 offset:13856
	v_cvt_pk_bf16_f32 v144, v92, v93
	s_waitcnt lgkmcnt(3)
	v_mfma_f32_32x32x16_bf16 v[96:111], v[64:67], v[128:131], v[112:127]
	v_add_f32_e32 v64, v93, v92
	v_add_f32_e32 v65, v95, v94
	v_cvt_pk_bf16_f32 v145, v94, v95
	v_add_f32_e32 v66, v173, v172
	v_add_f32_e32 v148, v66, v64
	v_add_f32_e32 v64, v175, v174
	v_add_f32_e32 v149, v64, v65
	s_waitcnt lgkmcnt(1)
	v_mfma_f32_32x32x16_bf16 v[64:79], v[84:87], v[128:131], v[112:127]
	ds_read_b128 v[92:95], v196 offset:9280
	v_cvt_pk_bf16_f32 v146, v172, v173
	v_cvt_pk_bf16_f32 v147, v174, v175
	v_mfma_f32_32x32x16_bf16 v[96:111], v[80:83], v[132:135], v[96:111]
	ds_read_b128 v[84:87], v196 offset:13888
	v_add_f32_e32 v80, v177, v176
	v_add_f32_e32 v150, v80, v148
	v_add_f32_e32 v80, v179, v178
	v_add_f32_e32 v151, v80, v149
	v_cvt_pk_bf16_f32 v148, v176, v177
	v_cvt_pk_bf16_f32 v149, v178, v179
	s_waitcnt lgkmcnt(2)
	v_mfma_f32_32x32x16_bf16 v[64:79], v[88:91], v[132:135], v[64:79]
	ds_read_b128 v[80:83], v196 offset:9312
	s_waitcnt vmcnt(2)
	ds_write_b128 v195, v[168:171]
	v_add_f32_e32 v88, v181, v180
	v_add_f32_e32 v152, v88, v150
	v_add_f32_e32 v88, v183, v182
	v_add_f32_e32 v153, v88, v151
	v_cvt_pk_bf16_f32 v150, v180, v181
	v_cvt_pk_bf16_f32 v151, v182, v183
	s_waitcnt lgkmcnt(3)
	v_mfma_f32_32x32x16_bf16 v[96:111], v[92:95], v[136:139], v[96:111]
	ds_read_b128 v[88:91], v196 offset:13920
	s_waitcnt vmcnt(1)
	ds_write2_b64 v244, v[164:165], v[166:167] offset1:2
	v_add_f32_e32 v92, v219, v218
	v_add_f32_e32 v93, v223, v222
	v_add_f32_e32 v92, v92, v152
	v_add_f32_e32 v93, v93, v153
	v_cvt_pk_bf16_f32 v152, v218, v219
	v_cvt_pk_bf16_f32 v153, v222, v223
	s_waitcnt lgkmcnt(4)
	v_mfma_f32_32x32x16_bf16 v[64:79], v[84:87], v[136:139], v[64:79]
	s_waitcnt vmcnt(0)
	ds_write2_b64 v245, v[160:161], v[162:163] offset0:128 offset1:130
	v_add_f32_e32 v84, v225, v224
	v_add_f32_e32 v85, v227, v226
	v_cvt_pk_bf16_f32 v154, v224, v225
	v_cvt_pk_bf16_f32 v155, v226, v227
	v_add_f32_e32 v84, v84, v92
	v_add_f32_e32 v85, v85, v93
	s_waitcnt lgkmcnt(4)
	v_mfma_f32_32x32x16_bf16 v[96:111], v[80:83], v[140:143], v[96:111]
	v_add_f32_e32 v80, v229, v228
	v_add_f32_e32 v81, v231, v230
	v_cvt_pk_bf16_f32 v156, v228, v229
	v_cvt_pk_bf16_f32 v157, v230, v231
	v_add_f32_e32 v80, v80, v84
	v_add_f32_e32 v81, v81, v85
	s_waitcnt lgkmcnt(2)
	v_mfma_f32_32x32x16_bf16 v[64:79], v[88:91], v[140:143], v[64:79]
	v_add_f32_e32 v82, v233, v232
	v_add_f32_e32 v80, v82, v80
	v_add_f32_e32 v82, v234, v159
	v_cvt_pk_bf16_f32 v158, v232, v233
	v_cvt_pk_bf16_f32 v159, v159, v234
	v_add_f32_e32 v81, v82, v81
	s_setprio 0
	v_add_f32_e32 v222, v81, v80
	v_fmac_f32_e32 v222, v221, v194
	s_andn2_b64 vcc, exec, s[8:9]
	s_cbranch_vccz .LBB0_468
; #define MFMA32(a, b, c) __builtin_amdgcn_mfma_f32_32x32x16_bf16((a), (b), (c), 0, 0, 0)
; #define SBAR() __builtin_amdgcn_sched_barrier(0)
; DI float max3f(float a, float b, float c) { return __builtin_fmaxf(__builtin_fmaxf(a, b), c); }
; #define AT_GLOADK(kt) do { rk = *(const u32x4*)(kg + (size_t)AT_PT(kt) * 64 * 2048); } while (0)
; #define AT_GLOADV(kt) do { rv0 = *(const u32x4*)(vg + AT_PT(kt) * 64); rv1 = *(const u32x4*)(vg + (size_t)64 * ROWS + AT_PT(kt) * 64); } while (0)
; DI void attn_step(const LAS unsigned char* Kb, const LAS unsigned char* Vb, f32x16& c0, f32x16& c1, f32x16& n0, f32x16& n1, bf16x8 (&pf)[2][2],
;                   f32x16 (&o)[4], f32x16& negm, float& mrun, float& lrun, const bf16x8 (&qf)[4]) {
;     ...
;     vf[0] = AT_VF(0); vf[1] = AT_VF(1); vf[2] = AT_VF(2);
;     float pm[4];
; #pragma unroll
;     for (int i = 0; i < 4; ++i) {
;         vf[(i + 3) % 4] = AT_VF(i + 3);
;         o[0] = MFMA32(vf[i % 4], pf[(i >> 1) & 1][i & 1], o[0]);
;         const float a = max3f(AT_C(8 * i), AT_C(8 * i + 1), AT_C(8 * i + 2)), b = max3f(AT_C(8 * i + 3), AT_C(8 * i + 4), AT_C(8 * i + 5));
;         pm[i] = max3f(a, b, __builtin_fmaxf(AT_C(8 * i + 6), AT_C(8 * i + 7)));
;         SBAR();
;     }
;     float mx = __builtin_fmaxf(__builtin_fmaxf(pm[0], pm[1]), __builtin_fmaxf(pm[2], pm[3]));
;     { auto rr = __builtin_amdgcn_permlane32_swap(__float_as_uint(mx), __float_as_uint(mx), false, false); mx = __builtin_fmaxf(__uint_as_float(rr[0]), __uint_as_float(rr[1])); }
;     float sc = 1.0f; bool need = false;
;     if (__builtin_expect(__any(mx > AT_THR), 0)) {
; DI void attn_unit(LAS unsigned char* lds, const bf16_t* QK, const bf16_t* VT, bf16_t* O, int mp, int h, int q0, int kt0, int kt1, int coff, int wid0) {
;     ...
;         __syncthreads();
;         { const int ktk = t + 3 < nkt ? t + 3 : nkt - 1; AT_GLOADK(kt0 + ktk); AT_GLOADV(kt0 + t + 1); }
.LBB0_460:
	s_min_u32 s8, s68, 0x100
	s_cmpk_gt_u32 s68, 0xfc
	s_cselect_b32 s9, s0, 0
	s_add_i32 s8, s8, s9
	s_lshl_b32 s8, s8, 18
	s_add_i32 s18, s8, 0xc0000
	s_cmpk_gt_u32 s68, 0xfe
	s_cselect_b32 s8, s0, 0
	s_add_i32 s8, s8, s68
	s_lshl_b32 s8, s8, 6
	v_lshl_add_u64 v[240:241], v[188:189], 0, s[18:19]
	s_add_i32 s18, s8, 64
	s_lshl_b64 s[8:9], s[18:19], 1
	s_waitcnt lgkmcnt(0)
	s_barrier
	ds_read_b128 v[80:83], v196 offset:18432
	ds_read_b128 v[84:87], v196 offset:18464
	ds_read_b128 v[88:91], v196 offset:18496
	ds_read_b128 v[92:95], v196 offset:18528
	v_lshl_add_u64 v[242:243], v[190:191], 0, s[8:9]
	global_load_dwordx4 v[168:171], v[240:241], off offset:2048
	global_load_dwordx4 v[164:167], v[242:243], off
	v_lshl_add_u64 v[240:241], v[192:193], 0, s[8:9]
	global_load_dwordx4 v[160:163], v[240:241], off
	s_waitcnt lgkmcnt(3)
	v_mfma_f32_32x32x16_bf16 v[48:63], v[80:83], v[144:147], v[48:63]
	ds_read_b128 v[172:175], v196 offset:23040
	v_max3_f32 v80, v96, v97, v98
	v_max3_f32 v81, v99, v100, v101
	v_max3_f32 v80, v80, v102, v103
	v_max3_f32 v81, v81, v104, v105
	s_waitcnt lgkmcnt(3)
	v_mfma_f32_32x32x16_bf16 v[48:63], v[84:87], v[148:151], v[48:63]
	ds_read_b128 v[176:179], v196 offset:23072
	v_max3_f32 v80, v80, v106, v107
	v_max3_f32 v81, v81, v108, v109
	v_max3_f32 v80, v80, v110, v111
	v_max3_f32 v81, v81, v64, v65
	s_waitcnt lgkmcnt(3)
	v_mfma_f32_32x32x16_bf16 v[48:63], v[88:91], v[152:155], v[48:63]
	ds_read_b128 v[180:183], v196 offset:23104
	v_max3_f32 v80, v80, v66, v67
	v_max3_f32 v81, v81, v68, v69
	v_max3_f32 v80, v80, v70, v71
	v_max3_f32 v81, v81, v72, v73
	s_waitcnt lgkmcnt(3)
	v_mfma_f32_32x32x16_bf16 v[48:63], v[92:95], v[156:159], v[48:63]
	ds_read_b128 v[248:251], v196 offset:23136
	v_max3_f32 v80, v80, v74, v75
	v_max3_f32 v81, v81, v76, v77
	v_max3_f32 v80, v80, v78, v79
	v_max_f32_e32 v80, v80, v81
	v_cmp_lt_f32_e32 vcc, s15, v80
	s_cmp_lg_u64 vcc, 0
	s_cselect_b64 s[8:9], -1, 0
	s_cbranch_vccnz .LBB0_469
; DI unsigned pk2(float lo, float hi) { f32x2 v = {lo, hi}; bf16x2_t b = __builtin_convertvector(v, bf16x2_t); return __builtin_bit_cast(unsigned, b); }
; #define MFMA32(a, b, c) __builtin_amdgcn_mfma_f32_32x32x16_bf16((a), (b), (c), 0, 0, 0)
; #define SBAR() __builtin_amdgcn_sched_barrier(0)
; #define AT_WRITEK(slot) do { *(LAS u32x4*)(lds + (slot) * AT_K + kst) = rk; } while (0)
; DI void attn_step(const LAS unsigned char* Kb, const LAS unsigned char* Vb, f32x16& c0, f32x16& c1, f32x16& n0, f32x16& n1, bf16x8 (&pf)[2][2],
;                   f32x16 (&o)[4], f32x16& negm, float& mrun, float& lrun, const bf16x8 (&qf)[4]) {
;     ...
;     __builtin_amdgcn_s_setprio(1);
; #pragma unroll
;     for (int i = 4; i < 16; ++i) {
;         if (i + 3 < 16) vf[(i + 3) % 4] = AT_VF(i + 3);
;         o[i >> 2] = MFMA32(vf[i % 4], pf[(i >> 1) & 1][i & 1], o[i >> 2]);
;         const int j = i - 4, e0 = j < 8 ? 3 * j : 24 + 2 * (j - 8), ne = j < 8 ? 3 : 2;
; #pragma unroll
;         for (int e = e0; e < e0 + ne; ++e) { if (e < 16) c0[e & 15] = __builtin_amdgcn_exp2f(c0[e & 15]); else c1[e & 15] = __builtin_amdgcn_exp2f(c1[e & 15]); }
;         SBAR();
;     }
;     bf16x8 kf[4];
;     kf[0] = AT_KF(0); kf[1] = AT_KF(1); kf[2] = AT_KF(2);
;     float ls0 = 0.f, ls1 = 0.f; unsigned pw[16];
; #pragma unroll
;     for (int i = 0; i < 8; ++i) {
;         if (i + 3 < 8) kf[(i + 3) % 4] = AT_KF(i + 3);
;         if (i & 1) n1 = MFMA32(kf[i % 4], qf[i >> 1], i < 2 ? negm : n1); else n0 = MFMA32(kf[i % 4], qf[i >> 1], i < 2 ? negm : n0);
;         ls0 += AT_C(4 * i) + AT_C(4 * i + 1); ls1 += AT_C(4 * i + 2) + AT_C(4 * i + 3);
;         pw[2 * i] = pk2(AT_C(4 * i), AT_C(4 * i + 1)); pw[2 * i + 1] = pk2(AT_C(4 * i + 2), AT_C(4 * i + 3));
;         SBAR();
;     }
; #pragma unroll
;     for (int kh = 0; kh < 2; ++kh)
; #pragma unroll
;         for (int s2 = 0; s2 < 2; ++s2) { const u32x4 w = (u32x4){pw[8 * kh + 4 * s2], pw[8 * kh + 4 * s2 + 1], pw[8 * kh + 4 * s2 + 2], pw[8 * kh + 4 * s2 + 3]}; pf[kh][s2] = __builtin_bit_cast(bf16x8, w); }
;     __builtin_amdgcn_s_setprio(0);
;     lrun = lrun * sc + (ls0 + ls1);
; DI void attn_unit(LAS unsigned char* lds, const bf16_t* QK, const bf16_t* VT, bf16_t* O, int mp, int h, int q0, int kt0, int kt1, int coff, int wid0) {
;     ...
;         AT_WRITEK(1); AT_WRITEV(1);
;         __syncthreads();
.LBB0_464:
	s_setprio 1
	s_waitcnt lgkmcnt(3)
	v_mfma_f32_32x32x16_bf16 v[32:47], v[172:175], v[144:147], v[32:47]
	ds_read_b128 v[80:83], v196 offset:27648
	v_exp_f32_e32 v172, v96
	v_exp_f32_e32 v173, v97
	v_exp_f32_e32 v174, v98
	s_waitcnt lgkmcnt(3)
	v_mfma_f32_32x32x16_bf16 v[32:47], v[176:179], v[148:151], v[32:47]
	ds_read_b128 v[84:87], v196 offset:27680
	v_exp_f32_e32 v175, v99
	v_exp_f32_e32 v176, v100
	v_exp_f32_e32 v177, v101
	s_waitcnt lgkmcnt(3)
	v_mfma_f32_32x32x16_bf16 v[32:47], v[180:183], v[152:155], v[32:47]
	ds_read_b128 v[88:91], v196 offset:27712
	v_exp_f32_e32 v178, v102
	v_exp_f32_e32 v179, v103
	v_exp_f32_e32 v180, v104
	s_waitcnt lgkmcnt(3)
	v_mfma_f32_32x32x16_bf16 v[32:47], v[248:251], v[156:159], v[32:47]
	ds_read_b128 v[92:95], v196 offset:27744
	v_exp_f32_e32 v181, v105
	v_exp_f32_e32 v182, v106
	v_exp_f32_e32 v183, v107
	s_waitcnt lgkmcnt(3)
	v_mfma_f32_32x32x16_bf16 v[16:31], v[80:83], v[144:147], v[16:31]
	ds_read_b128 v[80:83], v196 offset:32256
	v_exp_f32_e32 v239, v108
	v_exp_f32_e32 v218, v109
	v_exp_f32_e32 v219, v110
	s_waitcnt lgkmcnt(3)
	v_mfma_f32_32x32x16_bf16 v[16:31], v[84:87], v[148:151], v[16:31]
	ds_read_b128 v[84:87], v196 offset:32288
	v_exp_f32_e32 v221, v111
	v_exp_f32_e32 v224, v64
	v_exp_f32_e32 v225, v65
	s_waitcnt lgkmcnt(3)
	v_mfma_f32_32x32x16_bf16 v[16:31], v[88:91], v[152:155], v[16:31]
	ds_read_b128 v[88:91], v196 offset:32320
	v_exp_f32_e32 v226, v66
	v_exp_f32_e32 v227, v67
	v_exp_f32_e32 v228, v68
	s_waitcnt lgkmcnt(3)
	v_mfma_f32_32x32x16_bf16 v[16:31], v[92:95], v[156:159], v[16:31]
	ds_read_b128 v[64:67], v196 offset:32352
	v_exp_f32_e32 v229, v69
	v_exp_f32_e32 v230, v70
	v_exp_f32_e32 v231, v71
	s_waitcnt lgkmcnt(3)
	v_mfma_f32_32x32x16_bf16 v[0:15], v[80:83], v[144:147], v[0:15]
	v_exp_f32_e32 v232, v72
	v_exp_f32_e32 v233, v73
	s_waitcnt lgkmcnt(2)
	v_mfma_f32_32x32x16_bf16 v[0:15], v[84:87], v[148:151], v[0:15]
	v_exp_f32_e32 v234, v74
	v_exp_f32_e32 v235, v75
	s_waitcnt lgkmcnt(1)
	v_mfma_f32_32x32x16_bf16 v[0:15], v[88:91], v[152:155], v[0:15]
	v_exp_f32_e32 v236, v76
	v_exp_f32_e32 v237, v77
	s_waitcnt lgkmcnt(0)
	v_mfma_f32_32x32x16_bf16 v[0:15], v[64:67], v[156:159], v[0:15]
	v_exp_f32_e32 v159, v78
	v_exp_f32_e32 v238, v79
	ds_read_b128 v[64:67], v196
	ds_read_b128 v[80:83], v196 offset:32
	ds_read_b128 v[84:87], v196 offset:4608
	ds_read_b128 v[88:91], v196 offset:4640
	v_cvt_pk_bf16_f32 v148, v172, v173
	s_waitcnt lgkmcnt(3)
	v_mfma_f32_32x32x16_bf16 v[96:111], v[64:67], v[128:131], v[112:127]
	v_add_f32_e32 v64, v173, v172
	v_add_f32_e32 v65, v175, v174
	v_cvt_pk_bf16_f32 v149, v174, v175
	v_add_f32_e32 v66, v177, v176
	v_add_f32_e32 v144, v66, v64
	v_add_f32_e32 v64, v179, v178
	v_add_f32_e32 v145, v64, v65
	s_waitcnt lgkmcnt(1)
	v_mfma_f32_32x32x16_bf16 v[64:79], v[84:87], v[128:131], v[112:127]
	ds_read_b128 v[92:95], v196 offset:64
	v_cvt_pk_bf16_f32 v150, v176, v177
	v_cvt_pk_bf16_f32 v151, v178, v179
	v_mfma_f32_32x32x16_bf16 v[96:111], v[80:83], v[132:135], v[96:111]
	ds_read_b128 v[84:87], v196 offset:4672
	v_add_f32_e32 v80, v181, v180
	v_add_f32_e32 v146, v80, v144
	v_add_f32_e32 v80, v183, v182
	v_add_f32_e32 v147, v80, v145
	v_cvt_pk_bf16_f32 v144, v180, v181
	v_cvt_pk_bf16_f32 v145, v182, v183
	s_waitcnt lgkmcnt(2)
	v_mfma_f32_32x32x16_bf16 v[64:79], v[88:91], v[132:135], v[64:79]
	ds_read_b128 v[80:83], v196 offset:96
	s_waitcnt vmcnt(2)
	ds_write_b128 v195, v[168:171] offset:9216
	v_add_f32_e32 v88, v218, v239
	v_add_f32_e32 v152, v88, v146
	v_add_f32_e32 v88, v221, v219
	v_add_f32_e32 v153, v88, v147
	v_cvt_pk_bf16_f32 v146, v239, v218
	v_cvt_pk_bf16_f32 v147, v219, v221
	s_waitcnt lgkmcnt(3)
	v_mfma_f32_32x32x16_bf16 v[96:111], v[92:95], v[136:139], v[96:111]
	ds_read_b128 v[88:91], v196 offset:4704
	s_waitcnt vmcnt(1)
	ds_write2_b64 v246, v[164:165], v[166:167] offset1:2
	v_add_f32_e32 v92, v225, v224
	v_add_f32_e32 v93, v227, v226
	v_add_f32_e32 v92, v92, v152
	v_add_f32_e32 v93, v93, v153
	v_cvt_pk_bf16_f32 v152, v224, v225
	v_cvt_pk_bf16_f32 v153, v226, v227
	s_waitcnt lgkmcnt(4)
	v_mfma_f32_32x32x16_bf16 v[64:79], v[84:87], v[136:139], v[64:79]
	s_waitcnt vmcnt(0)
	ds_write2_b64 v247, v[160:161], v[162:163] offset0:128 offset1:130
	v_add_f32_e32 v84, v229, v228
	v_add_f32_e32 v85, v231, v230
	v_cvt_pk_bf16_f32 v154, v228, v229
	v_cvt_pk_bf16_f32 v155, v230, v231
	v_add_f32_e32 v84, v84, v92
	v_add_f32_e32 v85, v85, v93
	s_waitcnt lgkmcnt(4)
	v_mfma_f32_32x32x16_bf16 v[96:111], v[80:83], v[140:143], v[96:111]
	v_add_f32_e32 v80, v233, v232
	v_add_f32_e32 v81, v235, v234
	v_cvt_pk_bf16_f32 v156, v232, v233
	v_cvt_pk_bf16_f32 v157, v234, v235
	v_add_f32_e32 v80, v80, v84
	v_add_f32_e32 v81, v81, v85
	s_waitcnt lgkmcnt(2)
	v_mfma_f32_32x32x16_bf16 v[64:79], v[88:91], v[140:143], v[64:79]
	v_add_f32_e32 v82, v237, v236
	v_add_f32_e32 v80, v82, v80
	v_add_f32_e32 v82, v238, v159
	v_cvt_pk_bf16_f32 v158, v236, v237
	v_cvt_pk_bf16_f32 v159, v159, v238
	v_add_f32_e32 v81, v82, v81
	s_setprio 0
	v_add_f32_e32 v221, v81, v80
	v_fmac_f32_e32 v221, v222, v194
	s_andn2_b64 vcc, exec, s[8:9]
	s_cbranch_vccz .LBB0_470

; #define SBAR() __builtin_amdgcn_sched_barrier(0)
; DI void attn_step(const LAS unsigned char* Kb, const LAS unsigned char* Vb, f32x16& c0, f32x16& c1, f32x16& n0, f32x16& n1, bf16x8 (&pf)[2][2],
;                   f32x16 (&o)[4], f32x16& negm, float& mrun, float& lrun, const bf16x8 (&qf)[4]) {
;     ...
;     vf[0] = AT_VF(0); vf[1] = AT_VF(1); vf[2] = AT_VF(2);
;     float pm[4];
; #pragma unroll
;     for (int i = 0; i < 4; ++i) {
;         vf[(i + 3) % 4] = AT_VF(i + 3);
;         o[0] = MFMA32(vf[i % 4], pf[(i >> 1) & 1][i & 1], o[0]);
;         const float a = max3f(AT_C(8 * i), AT_C(8 * i + 1), AT_C(8 * i + 2)), b = max3f(AT_C(8 * i + 3), AT_C(8 * i + 4), AT_C(8 * i + 5));
;         pm[i] = max3f(a, b, __builtin_fmaxf(AT_C(8 * i + 6), AT_C(8 * i + 7)));
;         SBAR();
;     }
;     float mx = __builtin_fmaxf(__builtin_fmaxf(pm[0], pm[1]), __builtin_fmaxf(pm[2], pm[3]));
;     { auto rr = __builtin_amdgcn_permlane32_swap(__float_as_uint(mx), __float_as_uint(mx), false, false); mx = __builtin_fmaxf(__uint_as_float(rr[0]), __uint_as_float(rr[1])); }
;     float sc = 1.0f; bool need = false;
;     if (__builtin_expect(__any(mx > AT_THR), 0)) {
;         const float d = mx > AT_THR ? mx : 0.f;
; #pragma unroll
;         for (int r = 0; r < 16; ++r) { c0[r] -= d; c1[r] -= d; }
;         mrun += d; sc = __builtin_amdgcn_exp2f(-d); need = true;
; #pragma unroll
;         for (int r = 0; r < 16; ++r) negm[r] = -mrun;
;     }
;     asm volatile("" : "+v"(negm));
;     __builtin_amdgcn_s_setprio(1);
; #pragma unroll
;     for (int i = 4; i < 16; ++i) {
;         if (i + 3 < 16) vf[(i + 3) % 4] = AT_VF(i + 3);
;         o[i >> 2] = MFMA32(vf[i % 4], pf[(i >> 1) & 1][i & 1], o[i >> 2]);
;         const int j = i - 4, e0 = j < 8 ? 3 * j : 24 + 2 * (j - 8), ne = j < 8 ? 3 : 2;
; #pragma unroll
;         for (int e = e0; e < e0 + ne; ++e) { if (e < 16) c0[e & 15] = __builtin_amdgcn_exp2f(c0[e & 15]); else c1[e & 15] = __builtin_amdgcn_exp2f(c1[e & 15]); }
;         SBAR();
;     }
;     bf16x8 kf[4];
;     kf[0] = AT_KF(0); kf[1] = AT_KF(1); kf[2] = AT_KF(2);
;     float ls0 = 0.f, ls1 = 0.f; unsigned pw[16];
; #pragma unroll
;     for (int i = 0; i < 8; ++i) {
;         if (i + 3 < 8) kf[(i + 3) % 4] = AT_KF(i + 3);
;         if (i & 1) n1 = MFMA32(kf[i % 4], qf[i >> 1], i < 2 ? negm : n1); else n0 = MFMA32(kf[i % 4], qf[i >> 1], i < 2 ? negm : n0);
.Lg1_457:
	s_add_i32 s5, s68, 2
	s_min_u32 s8, s5, 0x103
	s_cmpk_gt_u32 s68, 0xfd
	s_cselect_b32 s9, s0, 0
	s_add_i32 s9, s9, s8
	s_lshl_b32 s18, s9, 18
	s_cmpk_gt_u32 s68, 0xff
	s_cselect_b32 s8, s0, 0
	s_add_i32 s8, s8, s68
	v_lshl_add_u64 v[240:241], v[188:189], 0, s[18:19]
	s_lshl_b32 s18, s8, 6
	s_lshl_b64 s[8:9], s[18:19], 1
	v_lshl_add_u64 v[242:243], v[190:191], 0, s[8:9]
	global_load_dwordx4 v[168:171], v[240:241], off offset:2048
	global_load_dwordx4 v[164:167], v[242:243], off
	v_lshl_add_u64 v[240:241], v[192:193], 0, s[8:9]
	global_load_dwordx4 v[160:163], v[240:241], off
	s_waitcnt lgkmcnt(3)
	v_mfma_f32_32x32x16_bf16 v[48:63], v[172:175], v[148:151], v[48:63]
	ds_read_b128 v[172:175], v196 offset:41472
	v_max3_f32 v80, v96, v97, v98
	v_max3_f32 v81, v99, v100, v101
	v_max3_f32 v80, v80, v102, v103
	v_max3_f32 v81, v81, v104, v105
	s_waitcnt lgkmcnt(3)
	v_mfma_f32_32x32x16_bf16 v[48:63], v[176:179], v[144:147], v[48:63]
	ds_read_b128 v[176:179], v196 offset:41504
	v_max3_f32 v80, v80, v106, v107
	v_max3_f32 v81, v81, v108, v109
	v_max3_f32 v80, v80, v110, v111
	v_max3_f32 v81, v81, v64, v65
	s_waitcnt lgkmcnt(3)
	v_mfma_f32_32x32x16_bf16 v[48:63], v[180:183], v[152:155], v[48:63]
	ds_read_b128 v[180:183], v196 offset:41536
	v_max3_f32 v80, v80, v66, v67
	v_max3_f32 v81, v81, v68, v69
	v_max3_f32 v80, v80, v70, v71
	v_max3_f32 v81, v81, v72, v73
	s_waitcnt lgkmcnt(3)
	v_mfma_f32_32x32x16_bf16 v[48:63], v[88:91], v[156:159], v[48:63]
	ds_read_b128 v[248:251], v196 offset:41568
	v_max3_f32 v80, v80, v74, v75
	v_max3_f32 v81, v81, v76, v77
	v_max3_f32 v80, v80, v78, v79
	v_max_f32_e32 v80, v80, v81
	v_cmp_lt_f32_e32 vcc, s15, v80
	s_cmp_lg_u64 vcc, 0
	s_cselect_b64 s[8:9], -1, 0
	s_cbranch_vccnz .Lg1_467
.Lg1_459:
	s_setprio 1
	s_waitcnt lgkmcnt(3)
	v_mfma_f32_32x32x16_bf16 v[32:47], v[172:175], v[148:151], v[32:47]
	ds_read_b128 v[80:83], v196 offset:46080
	v_exp_f32_e32 v92, v96
	v_exp_f32_e32 v93, v97
	v_exp_f32_e32 v94, v98
	s_waitcnt lgkmcnt(3)
	v_mfma_f32_32x32x16_bf16 v[32:47], v[176:179], v[144:147], v[32:47]
	ds_read_b128 v[84:87], v196 offset:46112
	v_exp_f32_e32 v95, v99
	v_exp_f32_e32 v172, v100
	v_exp_f32_e32 v173, v101
	s_waitcnt lgkmcnt(3)
	v_mfma_f32_32x32x16_bf16 v[32:47], v[180:183], v[152:155], v[32:47]
	ds_read_b128 v[96:99], v196 offset:46144
	v_exp_f32_e32 v174, v102
	v_exp_f32_e32 v175, v103
	v_exp_f32_e32 v176, v104
	s_waitcnt lgkmcnt(3)
	v_mfma_f32_32x32x16_bf16 v[32:47], v[248:251], v[156:159], v[32:47]
	ds_read_b128 v[100:103], v196 offset:46176
	v_exp_f32_e32 v177, v105
	v_exp_f32_e32 v178, v106
	v_exp_f32_e32 v179, v107
	s_waitcnt lgkmcnt(3)
	v_mfma_f32_32x32x16_bf16 v[16:31], v[80:83], v[148:151], v[16:31]
	ds_read_b128 v[104:107], v196 offset:50688
	v_exp_f32_e32 v180, v108
	v_exp_f32_e32 v181, v109
	v_exp_f32_e32 v182, v110
	s_waitcnt lgkmcnt(3)
	v_mfma_f32_32x32x16_bf16 v[16:31], v[84:87], v[144:147], v[16:31]
	ds_read_b128 v[80:83], v196 offset:50720
	v_exp_f32_e32 v183, v111
	v_exp_f32_e32 v218, v64
	v_exp_f32_e32 v219, v65
	s_waitcnt lgkmcnt(3)
	v_mfma_f32_32x32x16_bf16 v[16:31], v[96:99], v[152:155], v[16:31]
	ds_read_b128 v[96:99], v196 offset:50752
	v_exp_f32_e32 v222, v66
	v_exp_f32_e32 v223, v67
	v_exp_f32_e32 v224, v68
	s_waitcnt lgkmcnt(3)
	v_mfma_f32_32x32x16_bf16 v[16:31], v[100:103], v[156:159], v[16:31]
	ds_read_b128 v[64:67], v196 offset:50784
	v_exp_f32_e32 v225, v69
	v_exp_f32_e32 v226, v70
	v_exp_f32_e32 v227, v71
	s_waitcnt lgkmcnt(3)
	v_mfma_f32_32x32x16_bf16 v[0:15], v[104:107], v[148:151], v[0:15]
	v_exp_f32_e32 v228, v72
	v_exp_f32_e32 v229, v73
	s_waitcnt lgkmcnt(2)
	v_mfma_f32_32x32x16_bf16 v[0:15], v[80:83], v[144:147], v[0:15]
	v_exp_f32_e32 v230, v74
	v_exp_f32_e32 v231, v75
	s_waitcnt lgkmcnt(1)
	v_mfma_f32_32x32x16_bf16 v[0:15], v[96:99], v[152:155], v[0:15]
	v_exp_f32_e32 v232, v76
	v_exp_f32_e32 v233, v77
	s_waitcnt lgkmcnt(0)
	v_mfma_f32_32x32x16_bf16 v[0:15], v[64:67], v[156:159], v[0:15]
	v_exp_f32_e32 v159, v78
	v_exp_f32_e32 v234, v79
	ds_read_b128 v[64:67], v196 offset:9216
	ds_read_b128 v[80:83], v196 offset:9248
	ds_read_b128 v[84:87], v196 offset:13824
	ds_read_b128 v[88:91], v196 offset:13856
	v_cvt_pk_bf16_f32 v144, v92, v93
	s_waitcnt lgkmcnt(3)
	v_mfma_f32_32x32x16_bf16 v[96:111], v[64:67], v[128:131], v[112:127]
	v_add_f32_e32 v64, v93, v92
	v_add_f32_e32 v65, v95, v94
	v_cvt_pk_bf16_f32 v145, v94, v95
	v_add_f32_e32 v66, v173, v172
	v_add_f32_e32 v148, v66, v64
	v_add_f32_e32 v64, v175, v174
	v_add_f32_e32 v149, v64, v65
	s_waitcnt lgkmcnt(1)
	v_mfma_f32_32x32x16_bf16 v[64:79], v[84:87], v[128:131], v[112:127]
	ds_read_b128 v[92:95], v196 offset:9280
	s_waitcnt vmcnt(2)
	ds_write_b128 v195, v[168:171]
	v_cvt_pk_bf16_f32 v146, v172, v173
	v_cvt_pk_bf16_f32 v147, v174, v175
	v_mfma_f32_32x32x16_bf16 v[96:111], v[80:83], v[132:135], v[96:111]
	ds_read_b128 v[84:87], v196 offset:13888
	v_add_f32_e32 v80, v177, v176
	v_add_f32_e32 v150, v80, v148
	v_add_f32_e32 v80, v179, v178
	v_add_f32_e32 v151, v80, v149
	v_cvt_pk_bf16_f32 v148, v176, v177
	v_cvt_pk_bf16_f32 v149, v178, v179
	ds_read_b128 v[80:83], v196 offset:9312
	ds_read_b128 v[248:251], v196 offset:13920
	s_waitcnt vmcnt(1)
	ds_write2_b64 v244, v[164:165], v[166:167] offset1:2
	s_waitcnt lgkmcnt(6)
	v_mfma_f32_32x32x16_bf16 v[64:79], v[88:91], v[132:135], v[64:79]
	s_waitcnt vmcnt(0)
	ds_write2_b64 v245, v[160:161], v[162:163] offset0:128 offset1:130
	v_add_f32_e32 v88, v181, v180
	v_add_f32_e32 v152, v88, v150
	v_add_f32_e32 v88, v183, v182
	v_add_f32_e32 v153, v88, v151
	v_cvt_pk_bf16_f32 v150, v180, v181
	v_cvt_pk_bf16_f32 v151, v182, v183
	s_waitcnt lgkmcnt(0)
	s_barrier
	ds_read_b128 v[172:175], v196 offset:18432
	ds_read_b128 v[176:179], v196 offset:18464
	ds_read_b128 v[180:183], v196 offset:18496
	ds_read_b128 v[88:91], v196 offset:18528
	v_mfma_f32_32x32x16_bf16 v[96:111], v[92:95], v[136:139], v[96:111]
	v_add_f32_e32 v92, v219, v218
	v_add_f32_e32 v93, v223, v222
	v_add_f32_e32 v92, v92, v152
	v_add_f32_e32 v93, v93, v153
	v_cvt_pk_bf16_f32 v152, v218, v219
	v_cvt_pk_bf16_f32 v153, v222, v223
	v_mfma_f32_32x32x16_bf16 v[64:79], v[84:87], v[136:139], v[64:79]
	v_add_f32_e32 v84, v225, v224
	v_add_f32_e32 v85, v227, v226
	v_cvt_pk_bf16_f32 v154, v224, v225
	v_cvt_pk_bf16_f32 v155, v226, v227
	v_add_f32_e32 v84, v84, v92
	v_add_f32_e32 v85, v85, v93
	v_mfma_f32_32x32x16_bf16 v[96:111], v[80:83], v[140:143], v[96:111]
	v_add_f32_e32 v80, v229, v228
	v_add_f32_e32 v81, v231, v230
	v_cvt_pk_bf16_f32 v156, v228, v229
	v_cvt_pk_bf16_f32 v157, v230, v231
	v_add_f32_e32 v80, v80, v84
	v_add_f32_e32 v81, v81, v85
	v_mfma_f32_32x32x16_bf16 v[64:79], v[248:251], v[140:143], v[64:79]
	v_add_f32_e32 v82, v233, v232
	v_add_f32_e32 v80, v82, v80
	v_add_f32_e32 v82, v234, v159
	v_cvt_pk_bf16_f32 v158, v232, v233
	v_cvt_pk_bf16_f32 v159, v159, v234
	v_add_f32_e32 v81, v82, v81
	s_setprio 0
	v_add_f32_e32 v222, v81, v80
	v_fmac_f32_e32 v222, v221, v194
	s_andn2_b64 vcc, exec, s[8:9]
	s_cbranch_vccz .Lg1_468
; #define SBAR() __builtin_amdgcn_sched_barrier(0)
; DI void attn_step(const LAS unsigned char* Kb, const LAS unsigned char* Vb, f32x16& c0, f32x16& c1, f32x16& n0, f32x16& n1, bf16x8 (&pf)[2][2],
;                   f32x16 (&o)[4], f32x16& negm, float& mrun, float& lrun, const bf16x8 (&qf)[4]) {
;     ...
;     vf[0] = AT_VF(0); vf[1] = AT_VF(1); vf[2] = AT_VF(2);
;     float pm[4];
; #pragma unroll
;     for (int i = 0; i < 4; ++i) {
;         vf[(i + 3) % 4] = AT_VF(i + 3);
;         o[0] = MFMA32(vf[i % 4], pf[(i >> 1) & 1][i & 1], o[0]);
;         const float a = max3f(AT_C(8 * i), AT_C(8 * i + 1), AT_C(8 * i + 2)), b = max3f(AT_C(8 * i + 3), AT_C(8 * i + 4), AT_C(8 * i + 5));
;         pm[i] = max3f(a, b, __builtin_fmaxf(AT_C(8 * i + 6), AT_C(8 * i + 7)));
;         SBAR();
;     }
;     float mx = __builtin_fmaxf(__builtin_fmaxf(pm[0], pm[1]), __builtin_fmaxf(pm[2], pm[3]));
;     { auto rr = __builtin_amdgcn_permlane32_swap(__float_as_uint(mx), __float_as_uint(mx), false, false); mx = __builtin_fmaxf(__uint_as_float(rr[0]), __uint_as_float(rr[1])); }
;     float sc = 1.0f; bool need = false;
;     if (__builtin_expect(__any(mx > AT_THR), 0)) {
;         const float d = mx > AT_THR ? mx : 0.f;
; #pragma unroll
;         for (int r = 0; r < 16; ++r) { c0[r] -= d; c1[r] -= d; }
;         mrun += d; sc = __builtin_amdgcn_exp2f(-d); need = true;
; #pragma unroll
;         for (int r = 0; r < 16; ++r) negm[r] = -mrun;
;     }
;     asm volatile("" : "+v"(negm));
;     __builtin_amdgcn_s_setprio(1);
; #pragma unroll
;     for (int i = 4; i < 16; ++i) {
;         if (i + 3 < 16) vf[(i + 3) % 4] = AT_VF(i + 3);
;         o[i >> 2] = MFMA32(vf[i % 4], pf[(i >> 1) & 1][i & 1], o[i >> 2]);
;         const int j = i - 4, e0 = j < 8 ? 3 * j : 24 + 2 * (j - 8), ne = j < 8 ? 3 : 2;
; #pragma unroll
;         for (int e = e0; e < e0 + ne; ++e) { if (e < 16) c0[e & 15] = __builtin_amdgcn_exp2f(c0[e & 15]); else c1[e & 15] = __builtin_amdgcn_exp2f(c1[e & 15]); }
;         SBAR();
;     }
;     bf16x8 kf[4];
;     kf[0] = AT_KF(0); kf[1] = AT_KF(1); kf[2] = AT_KF(2);
;     float ls0 = 0.f, ls1 = 0.f; unsigned pw[16];
; #pragma unroll
;     for (int i = 0; i < 8; ++i) {
;         if (i + 3 < 8) kf[(i + 3) % 4] = AT_KF(i + 3);
;         if (i & 1) n1 = MFMA32(kf[i % 4], qf[i >> 1], i < 2 ? negm : n1); else n0 = MFMA32(kf[i % 4], qf[i >> 1], i < 2 ? negm : n0);
.Lg1_460:
	s_min_u32 s8, s68, 0x100
	s_cmpk_gt_u32 s68, 0xfc
	s_cselect_b32 s9, s0, 0
	s_add_i32 s8, s8, s9
	s_lshl_b32 s8, s8, 18
	s_add_i32 s18, s8, 0xc0000
	s_cmpk_gt_u32 s68, 0xfe
	s_cselect_b32 s8, s0, 0
	s_add_i32 s8, s8, s68
	s_lshl_b32 s8, s8, 6
	v_lshl_add_u64 v[240:241], v[188:189], 0, s[18:19]
	s_add_i32 s18, s8, 64
	s_lshl_b64 s[8:9], s[18:19], 1
	v_lshl_add_u64 v[242:243], v[190:191], 0, s[8:9]
	global_load_dwordx4 v[168:171], v[240:241], off offset:2048
	global_load_dwordx4 v[164:167], v[242:243], off
	v_lshl_add_u64 v[240:241], v[192:193], 0, s[8:9]
	global_load_dwordx4 v[160:163], v[240:241], off
	s_waitcnt lgkmcnt(3)
	v_mfma_f32_32x32x16_bf16 v[48:63], v[172:175], v[144:147], v[48:63]
	ds_read_b128 v[172:175], v196 offset:23040
	v_max3_f32 v80, v96, v97, v98
	v_max3_f32 v81, v99, v100, v101
	v_max3_f32 v80, v80, v102, v103
	v_max3_f32 v81, v81, v104, v105
	s_waitcnt lgkmcnt(3)
	v_mfma_f32_32x32x16_bf16 v[48:63], v[176:179], v[148:151], v[48:63]
	ds_read_b128 v[176:179], v196 offset:23072
	v_max3_f32 v80, v80, v106, v107
	v_max3_f32 v81, v81, v108, v109
	v_max3_f32 v80, v80, v110, v111
	v_max3_f32 v81, v81, v64, v65
	s_waitcnt lgkmcnt(3)
	v_mfma_f32_32x32x16_bf16 v[48:63], v[180:183], v[152:155], v[48:63]
	ds_read_b128 v[180:183], v196 offset:23104
	v_max3_f32 v80, v80, v66, v67
	v_max3_f32 v81, v81, v68, v69
	v_max3_f32 v80, v80, v70, v71
	v_max3_f32 v81, v81, v72, v73
	s_waitcnt lgkmcnt(3)
	v_mfma_f32_32x32x16_bf16 v[48:63], v[88:91], v[156:159], v[48:63]
	ds_read_b128 v[248:251], v196 offset:23136
	v_max3_f32 v80, v80, v74, v75
	v_max3_f32 v81, v81, v76, v77
	v_max3_f32 v80, v80, v78, v79
	v_max_f32_e32 v80, v80, v81
	v_cmp_lt_f32_e32 vcc, s15, v80
	s_cmp_lg_u64 vcc, 0
	s_cselect_b64 s[8:9], -1, 0
	s_cbranch_vccnz .Lg1_469
.Lg1_464:
	s_setprio 1
	s_waitcnt lgkmcnt(3)
	v_mfma_f32_32x32x16_bf16 v[32:47], v[172:175], v[144:147], v[32:47]
	ds_read_b128 v[80:83], v196 offset:27648
	v_exp_f32_e32 v172, v96
	v_exp_f32_e32 v173, v97
	v_exp_f32_e32 v174, v98
	s_waitcnt lgkmcnt(3)
	v_mfma_f32_32x32x16_bf16 v[32:47], v[176:179], v[148:151], v[32:47]
	ds_read_b128 v[84:87], v196 offset:27680
	v_exp_f32_e32 v175, v99
	v_exp_f32_e32 v176, v100
	v_exp_f32_e32 v177, v101
	s_waitcnt lgkmcnt(3)
	v_mfma_f32_32x32x16_bf16 v[32:47], v[180:183], v[152:155], v[32:47]
	ds_read_b128 v[88:91], v196 offset:27712
	v_exp_f32_e32 v178, v102
	v_exp_f32_e32 v179, v103
	v_exp_f32_e32 v180, v104
	s_waitcnt lgkmcnt(3)
	v_mfma_f32_32x32x16_bf16 v[32:47], v[248:251], v[156:159], v[32:47]
	ds_read_b128 v[92:95], v196 offset:27744
	v_exp_f32_e32 v181, v105
	v_exp_f32_e32 v182, v106
	v_exp_f32_e32 v183, v107
	s_waitcnt lgkmcnt(3)
	v_mfma_f32_32x32x16_bf16 v[16:31], v[80:83], v[144:147], v[16:31]
	ds_read_b128 v[80:83], v196 offset:32256
	v_exp_f32_e32 v239, v108
	v_exp_f32_e32 v218, v109
	v_exp_f32_e32 v219, v110
	s_waitcnt lgkmcnt(3)
	v_mfma_f32_32x32x16_bf16 v[16:31], v[84:87], v[148:151], v[16:31]
	ds_read_b128 v[84:87], v196 offset:32288
	v_exp_f32_e32 v221, v111
	v_exp_f32_e32 v224, v64
	v_exp_f32_e32 v225, v65
	s_waitcnt lgkmcnt(3)
	v_mfma_f32_32x32x16_bf16 v[16:31], v[88:91], v[152:155], v[16:31]
	ds_read_b128 v[88:91], v196 offset:32320
	v_exp_f32_e32 v226, v66
	v_exp_f32_e32 v227, v67
	v_exp_f32_e32 v228, v68
	s_waitcnt lgkmcnt(3)
	v_mfma_f32_32x32x16_bf16 v[16:31], v[92:95], v[156:159], v[16:31]
	ds_read_b128 v[64:67], v196 offset:32352
	v_exp_f32_e32 v229, v69
	v_exp_f32_e32 v230, v70
	v_exp_f32_e32 v231, v71
	s_waitcnt lgkmcnt(3)
	v_mfma_f32_32x32x16_bf16 v[0:15], v[80:83], v[144:147], v[0:15]
	v_exp_f32_e32 v232, v72
	v_exp_f32_e32 v233, v73
	s_waitcnt lgkmcnt(2)
	v_mfma_f32_32x32x16_bf16 v[0:15], v[84:87], v[148:151], v[0:15]
	v_exp_f32_e32 v234, v74
	v_exp_f32_e32 v235, v75
	s_waitcnt lgkmcnt(1)
	v_mfma_f32_32x32x16_bf16 v[0:15], v[88:91], v[152:155], v[0:15]
	v_exp_f32_e32 v236, v76
	v_exp_f32_e32 v237, v77
	s_waitcnt lgkmcnt(0)
	v_mfma_f32_32x32x16_bf16 v[0:15], v[64:67], v[156:159], v[0:15]
	v_exp_f32_e32 v159, v78
	v_exp_f32_e32 v238, v79
	ds_read_b128 v[64:67], v196
	ds_read_b128 v[80:83], v196 offset:32
	ds_read_b128 v[84:87], v196 offset:4608
	ds_read_b128 v[88:91], v196 offset:4640
	v_cvt_pk_bf16_f32 v148, v172, v173
	s_waitcnt lgkmcnt(3)
	v_mfma_f32_32x32x16_bf16 v[96:111], v[64:67], v[128:131], v[112:127]
	v_add_f32_e32 v64, v173, v172
	v_add_f32_e32 v65, v175, v174
	v_cvt_pk_bf16_f32 v149, v174, v175
	v_add_f32_e32 v66, v177, v176
	v_add_f32_e32 v144, v66, v64
	v_add_f32_e32 v64, v179, v178
	v_add_f32_e32 v145, v64, v65
	s_waitcnt lgkmcnt(1)
	v_mfma_f32_32x32x16_bf16 v[64:79], v[84:87], v[128:131], v[112:127]
	ds_read_b128 v[92:95], v196 offset:64
	s_waitcnt vmcnt(2)
	ds_write_b128 v195, v[168:171] offset:9216
	v_cvt_pk_bf16_f32 v150, v176, v177
	v_cvt_pk_bf16_f32 v151, v178, v179
	v_mfma_f32_32x32x16_bf16 v[96:111], v[80:83], v[132:135], v[96:111]
	ds_read_b128 v[84:87], v196 offset:4672
	v_add_f32_e32 v80, v181, v180
	v_add_f32_e32 v146, v80, v144
	v_add_f32_e32 v80, v183, v182
	v_add_f32_e32 v147, v80, v145
	v_cvt_pk_bf16_f32 v144, v180, v181
	v_cvt_pk_bf16_f32 v145, v182, v183
	ds_read_b128 v[80:83], v196 offset:96
	ds_read_b128 v[248:251], v196 offset:4704
	s_waitcnt vmcnt(1)
	ds_write2_b64 v246, v[164:165], v[166:167] offset1:2
	s_waitcnt lgkmcnt(6)
	v_mfma_f32_32x32x16_bf16 v[64:79], v[88:91], v[132:135], v[64:79]
	s_waitcnt vmcnt(0)
	ds_write2_b64 v247, v[160:161], v[162:163] offset0:128 offset1:130
	v_add_f32_e32 v88, v218, v239
	v_add_f32_e32 v152, v88, v146
	v_add_f32_e32 v88, v221, v219
	v_add_f32_e32 v153, v88, v147
	v_cvt_pk_bf16_f32 v146, v239, v218
	v_cvt_pk_bf16_f32 v147, v219, v221
	s_waitcnt lgkmcnt(0)
	s_barrier
	ds_read_b128 v[172:175], v196 offset:36864
	ds_read_b128 v[176:179], v196 offset:36896
	ds_read_b128 v[180:183], v196 offset:36928
	ds_read_b128 v[88:91], v196 offset:36960
	v_mfma_f32_32x32x16_bf16 v[96:111], v[92:95], v[136:139], v[96:111]
	v_add_f32_e32 v92, v225, v224
	v_add_f32_e32 v93, v227, v226
	v_add_f32_e32 v92, v92, v152
	v_add_f32_e32 v93, v93, v153
	v_cvt_pk_bf16_f32 v152, v224, v225
	v_cvt_pk_bf16_f32 v153, v226, v227
	v_mfma_f32_32x32x16_bf16 v[64:79], v[84:87], v[136:139], v[64:79]
	v_add_f32_e32 v84, v229, v228
	v_add_f32_e32 v85, v231, v230
	v_cvt_pk_bf16_f32 v154, v228, v229
	v_cvt_pk_bf16_f32 v155, v230, v231
	v_add_f32_e32 v84, v84, v92
	v_add_f32_e32 v85, v85, v93
	v_mfma_f32_32x32x16_bf16 v[96:111], v[80:83], v[140:143], v[96:111]
	v_add_f32_e32 v80, v233, v232
	v_add_f32_e32 v81, v235, v234
	v_cvt_pk_bf16_f32 v156, v232, v233
	v_cvt_pk_bf16_f32 v157, v234, v235
	v_add_f32_e32 v80, v80, v84
	v_add_f32_e32 v81, v81, v85
	v_mfma_f32_32x32x16_bf16 v[64:79], v[248:251], v[140:143], v[64:79]
	v_add_f32_e32 v82, v237, v236
	v_add_f32_e32 v80, v82, v80
	v_add_f32_e32 v82, v238, v159
	v_cvt_pk_bf16_f32 v158, v236, v237
	v_cvt_pk_bf16_f32 v159, v159, v238
	v_add_f32_e32 v81, v82, v81
	s_setprio 0
	v_add_f32_e32 v221, v81, v80
	v_fmac_f32_e32 v221, v222, v194
	s_andn2_b64 vcc, exec, s[8:9]
	s_cbranch_vccz .Lg1_470
